# scan_rwkv scanner waves: out/state base pointers loaded once before the segment loop (no s_load+wait per segment), all preamble LDS reads issued before the first wait, 8-step sample body hand-schedule
# speedup vs baseline: 1.0065x; 1.0006x over previous
.LBB0_1621:
	s_waitcnt lgkmcnt(0)
	s_add_u32 s14, s8, 0x3fa00000
	s_addc_u32 s15, s9, 0
	s_waitcnt lgkmcnt(0)
	s_barrier
	s_cmp_gt_i32 s40, 0
	v_and_b32_e32 v38, 15, v173
	s_cselect_b64 s[20:21], -1, 0
	s_cmp_lt_i32 s40, 1
	v_lshlrev_b32_e32 v40, 2, v43
	s_cbranch_scc1 .LBB0_1658
	s_lshl_b64 s[22:23], s[90:91], 11
	s_lshl_b64 s[24:25], s[90:91], 6
	s_add_i32 s3, 0, 0x1c000
	s_add_i32 s52, 0, 0x18000
	s_add_i32 s41, s40, -1
	s_add_u32 s42, s8, 0x33400000
	s_addc_u32 s43, s9, 0
	v_lshrrev_b32_e32 v0, 4, v2
	s_add_u32 s44, s8, 0x586c0000
	v_lshl_or_b32 v58, s2, 2, v0
	s_addc_u32 s45, s9, 0
	v_lshlrev_b32_e32 v0, 4, v58
	v_and_b32_e32 v2, 12, v38
	s_add_u32 s46, s8, 0x4c6c0000
	v_add3_u32 v59, s3, v0, v2
	v_lshlrev_b32_e32 v0, 8, v58
	v_lshlrev_b32_e32 v2, 4, v38
	s_addc_u32 s48, s9, 0
	s_lshl_b32 s2, s2, 10
	v_add3_u32 v60, s52, v0, v2
	s_add_i32 s49, s2, 0
	s_add_i32 s52, s52, s2
	v_readlane_b32 s2, v253, 53
	v_mov_b32_e32 v41, v1
	v_lshl_add_u32 v61, v43, 4, s3
	s_mul_i32 s2, s2, s38
	v_readlane_b32 s3, v253, 52
	v_lshlrev_b32_e32 v0, 6, v58
	v_lshl_add_u64 v[44:45], s[14:15], 0, v[40:41]
	v_lshrrev_b32_e32 v41, 4, v43
	s_sub_i32 s54, s3, s2
	s_not_b32 s2, s38
	v_readlane_b32 s3, v253, 2
	v_lshlrev_b32_e32 v42, 2, v38
	v_lshlrev_b32_e32 v46, 12, v41
	v_mov_b32_e32 v47, v1
	s_mul_i32 s55, s3, s2
	v_mov_b32_e32 v2, v1
	v_mov_b32_e32 v3, v1
	v_mov_b32_e32 v4, v1
	v_mov_b32_e32 v5, v1
	s_mov_b32 s57, 0
	s_movk_i32 s58, 0xf000
	s_movk_i32 s59, 0xc000
	v_lshlrev_b32_e32 v48, 2, v0
	v_lshlrev_b32_e32 v0, 2, v40
	v_lshlrev_b32_e32 v50, 2, v38
	v_readlane_b32 s60, v253, 3
	s_load_dwordx2 s[64:65], s[0:1], 0x1a8
	s_load_dwordx2 s[70:71], s[0:1], 0x10
	s_waitcnt lgkmcnt(0)
	s_branch .LBB0_1625

.LBB0_1625:
	s_mov_b64 s[26:27], -1
	s_and_b64 vcc, exec, s[12:13]
	s_cbranch_vccz .LBB0_1637
	s_cmp_ge_i32 s57, s38
	s_cselect_b64 s[30:31], -1, 0
	s_and_b64 vcc, exec, s[30:31]
	s_mov_b64 s[36:37], -1
	s_cbranch_vccz .LBB0_1653
	v_readlane_b32 s2, v253, 54
	s_mul_i32 s2, s2, s38
	s_add_i32 s3, s2, s60
	s_ashr_i32 s2, s3, 6
	s_bfe_u32 s28, s3, 0x40002
	s_ashr_i32 s3, s2, 31
	s_mov_b64 s[4:5], s[70:71]
	s_mov_b64 s[18:19], s[64:65]
	s_lshl_b64 s[2:3], s[2:3], 4
	s_add_u32 s2, s2, s22
	s_addc_u32 s29, s3, s23
	s_or_b32 s28, s2, s28
	s_and_b32 s2, s54, 48
	s_lshl_b64 s[28:29], s[28:29], 14
	s_waitcnt lgkmcnt(0)
	s_add_u32 s3, s18, s28
	s_addc_u32 s18, s19, s29
	s_lshl_b32 s19, s2, 8
	s_add_u32 s3, s3, s19
	s_addc_u32 s18, s18, 0
	s_add_u32 s28, s3, 0x4aba400
	s_addc_u32 s29, s18, 0
	s_cmp_eq_u64 s[4:5], 0
	s_cselect_b64 s[34:35], -1, 0
	v_mov_b64_e32 v[36:37], v[4:5]
	v_mov_b64_e32 v[34:35], v[2:3]
	s_cbranch_execz .LBB0_1654

.LBB0_1630:
	s_mulk_i32 s3, 0x6000
	s_add_i32 s3, s3, 0
	v_lshl_add_u32 v51, v42, 2, s3
	v_add_u32_e32 v6, s2, v58
	ds_read_b128 v[68:71], v51 offset:768
	ds_read_b128 v[54:57], v51 offset:512
	v_lshl_add_u32 v62, v6, 2, s3
	ds_read_b128 v[64:67], v51 offset:256
	ds_read2st64_b32 v[52:53], v62 offset0:5 offset1:11
	ds_read_b128 v[30:33], v51 offset:1024
	ds_read_b128 v[22:25], v51
	ds_read_b128 v[6:9], v51 offset:1536
	ds_read_b128 v[18:21], v51 offset:1792
	ds_read_b128 v[14:17], v51 offset:2048
	ds_read_b128 v[26:29], v51 offset:2304
	ds_read_b128 v[10:13], v51 offset:2560
	s_add_i32 s4, s58, 0x1000
	s_and_b32 s4, s4, 0x1000
	v_add_u32_e32 v49, s4, v59
	s_waitcnt lgkmcnt(10)
	v_pk_mul_f32 v[70:71], v[36:37], v[70:71]
	s_waitcnt lgkmcnt(7)
	v_pk_mul_f32 v[56:57], v[56:57], v[52:53] op_sel_hi:[1,0]
	v_pk_fma_f32 v[68:69], v[34:35], v[68:69], v[70:71]
	v_pk_mul_f32 v[72:73], v[54:55], v[52:53] op_sel_hi:[1,0]
	v_pk_fma_f32 v[54:55], v[36:37], v[66:67], v[56:57]
	v_add_f32_e32 v63, v68, v69
	v_pk_fma_f32 v[56:57], v[34:35], v[64:65], v[72:73]
	s_waitcnt lgkmcnt(0)
	s_mov_b64 s[34:35], -1
	s_and_b64 vcc, exec, s[30:31]
	s_cbranch_vccz .LBB0_1632
	s_mov_b64 s[34:35], 0
	v_add_f32_dpp v234, v63, v63 quad_perm:[1,0,3,2] row_mask:0xf bank_mask:0xf bound_ctrl:1
	v_mov_b32_e32 v240, v53
	s_nop 0
	v_add_f32_dpp v234, v234, v234 quad_perm:[2,3,0,1] row_mask:0xf bank_mask:0xf bound_ctrl:1
	s_nop 1
	v_add_f32_dpp v234, v234, v234 row_half_mirror row_mask:0xf bank_mask:0xf bound_ctrl:1
	s_nop 1
	v_add_f32_dpp v234, v234, v234 row_mirror row_mask:0xf bank_mask:0xf bound_ctrl:1
	v_pk_fma_f32 v[36:37], v[32:33], v[234:235], v[54:55] op_sel_hi:[1,0,1]
	v_pk_fma_f32 v[34:35], v[30:31], v[234:235], v[56:57] op_sel_hi:[1,0,1]
	ds_read_b128 v[224:227], v51 offset:3840
	s_waitcnt lgkmcnt(6)
	v_pk_mul_f32 v[232:233], v[28:29], v[36:37]
	v_pk_fma_f32 v[232:233], v[26:27], v[34:35], v[232:233]
	ds_read_b128 v[64:67], v51 offset:3328
	ds_read_b128 v[68:71], v51 offset:3584
	v_add_f32_e32 v234, v232, v233
	v_pk_mul_f32 v[236:237], v[24:25], v[36:37]
	v_pk_fma_f32 v[236:237], v[22:23], v[34:35], v[236:237]
	v_add_f32_dpp v234, v234, v234 quad_perm:[1,0,3,2] row_mask:0xf bank_mask:0xf bound_ctrl:1
	s_waitcnt lgkmcnt(5)
	v_pk_mul_f32 v[228:229], v[18:19], v[34:35]
	v_add_f32_e32 v238, v236, v237
	v_add_f32_dpp v234, v234, v234 quad_perm:[2,3,0,1] row_mask:0xf bank_mask:0xf bound_ctrl:1
	v_pk_mul_f32 v[230:231], v[20:21], v[36:37]
	v_pk_fma_f32 v[56:57], v[14:15], v[240:241], v[228:229] op_sel_hi:[1,0,1]
	v_add_f32_dpp v234, v234, v234 row_half_mirror row_mask:0xf bank_mask:0xf bound_ctrl:1
	v_pk_fma_f32 v[54:55], v[16:17], v[240:241], v[230:231] op_sel_hi:[1,0,1]
	v_add_f32_dpp v238, v238, v238 quad_perm:[1,0,3,2] row_mask:0xf bank_mask:0xf bound_ctrl:1
	v_add_f32_dpp v234, v234, v234 row_mirror row_mask:0xf bank_mask:0xf bound_ctrl:1
	ds_read_b32 v242, v62 offset:4352
	ds_read_b128 v[30:33], v51 offset:4096
	ds_read_b128 v[22:25], v51 offset:3072
	s_waitcnt lgkmcnt(7)
	v_pk_fma_f32 v[36:37], v[12:13], v[234:235], v[54:55] op_sel_hi:[1,0,1]
	v_pk_fma_f32 v[34:35], v[10:11], v[234:235], v[56:57] op_sel_hi:[1,0,1]
	v_add_f32_dpp v238, v238, v238 quad_perm:[2,3,0,1] row_mask:0xf bank_mask:0xf bound_ctrl:1
	ds_write_b32 v49, v238
	ds_read_b128 v[26:29], v51 offset:5376
	s_waitcnt lgkmcnt(6)
	v_pk_mul_f32 v[232:233], v[226:227], v[36:37]
	v_pk_fma_f32 v[232:233], v[224:225], v[34:35], v[232:233]
	ds_read_b128 v[18:21], v51 offset:4864
	ds_read_b128 v[14:17], v51 offset:5120
	v_add_f32_e32 v234, v232, v233
	v_pk_mul_f32 v[236:237], v[8:9], v[36:37]
	v_pk_fma_f32 v[236:237], v[6:7], v[34:35], v[236:237]
	v_add_f32_dpp v234, v234, v234 quad_perm:[1,0,3,2] row_mask:0xf bank_mask:0xf bound_ctrl:1
	s_waitcnt lgkmcnt(5)
	v_pk_mul_f32 v[228:229], v[64:65], v[34:35]
	v_add_f32_e32 v238, v236, v237
	v_add_f32_dpp v234, v234, v234 quad_perm:[2,3,0,1] row_mask:0xf bank_mask:0xf bound_ctrl:1
	v_pk_mul_f32 v[230:231], v[66:67], v[36:37]
	v_pk_fma_f32 v[56:57], v[68:69], v[242:243], v[228:229] op_sel_hi:[1,0,1]
	v_add_f32_dpp v234, v234, v234 row_half_mirror row_mask:0xf bank_mask:0xf bound_ctrl:1
	v_pk_fma_f32 v[54:55], v[70:71], v[242:243], v[230:231] op_sel_hi:[1,0,1]
	v_add_f32_dpp v238, v238, v238 quad_perm:[1,0,3,2] row_mask:0xf bank_mask:0xf bound_ctrl:1
	v_add_f32_dpp v234, v234, v234 row_mirror row_mask:0xf bank_mask:0xf bound_ctrl:1
	ds_read_b32 v240, v62 offset:5888
	ds_read_b128 v[10:13], v51 offset:5632
	ds_read_b128 v[6:9], v51 offset:4608
	s_waitcnt lgkmcnt(7)
	v_pk_fma_f32 v[36:37], v[32:33], v[234:235], v[54:55] op_sel_hi:[1,0,1]
	v_pk_fma_f32 v[34:35], v[30:31], v[234:235], v[56:57] op_sel_hi:[1,0,1]
	v_add_f32_dpp v238, v238, v238 quad_perm:[2,3,0,1] row_mask:0xf bank_mask:0xf bound_ctrl:1
	ds_write_b32 v49, v238 offset:256
	ds_read_b128 v[224:227], v51 offset:6912
	s_waitcnt lgkmcnt(6)
	v_pk_mul_f32 v[232:233], v[28:29], v[36:37]
	v_pk_fma_f32 v[232:233], v[26:27], v[34:35], v[232:233]
	ds_read_b128 v[64:67], v51 offset:6400
	ds_read_b128 v[68:71], v51 offset:6656
	v_add_f32_e32 v234, v232, v233
	v_pk_mul_f32 v[236:237], v[24:25], v[36:37]
	v_pk_fma_f32 v[236:237], v[22:23], v[34:35], v[236:237]
	v_add_f32_dpp v234, v234, v234 quad_perm:[1,0,3,2] row_mask:0xf bank_mask:0xf bound_ctrl:1
	s_waitcnt lgkmcnt(5)
	v_pk_mul_f32 v[228:229], v[18:19], v[34:35]
	v_add_f32_e32 v238, v236, v237
	v_add_f32_dpp v234, v234, v234 quad_perm:[2,3,0,1] row_mask:0xf bank_mask:0xf bound_ctrl:1
	v_pk_mul_f32 v[230:231], v[20:21], v[36:37]
	v_pk_fma_f32 v[56:57], v[14:15], v[240:241], v[228:229] op_sel_hi:[1,0,1]
	v_add_f32_dpp v234, v234, v234 row_half_mirror row_mask:0xf bank_mask:0xf bound_ctrl:1
	v_pk_fma_f32 v[54:55], v[16:17], v[240:241], v[230:231] op_sel_hi:[1,0,1]
	v_add_f32_dpp v238, v238, v238 quad_perm:[1,0,3,2] row_mask:0xf bank_mask:0xf bound_ctrl:1
	v_add_f32_dpp v234, v234, v234 row_mirror row_mask:0xf bank_mask:0xf bound_ctrl:1
	ds_read_b32 v242, v62 offset:7424
	ds_read_b128 v[30:33], v51 offset:7168
	ds_read_b128 v[22:25], v51 offset:6144
	s_waitcnt lgkmcnt(7)
	v_pk_fma_f32 v[36:37], v[12:13], v[234:235], v[54:55] op_sel_hi:[1,0,1]
	v_pk_fma_f32 v[34:35], v[10:11], v[234:235], v[56:57] op_sel_hi:[1,0,1]
	v_add_f32_dpp v238, v238, v238 quad_perm:[2,3,0,1] row_mask:0xf bank_mask:0xf bound_ctrl:1
	ds_write_b32 v49, v238 offset:512
	ds_read_b128 v[26:29], v51 offset:8448
	s_waitcnt lgkmcnt(6)
	v_pk_mul_f32 v[232:233], v[226:227], v[36:37]
	v_pk_fma_f32 v[232:233], v[224:225], v[34:35], v[232:233]
	ds_read_b128 v[18:21], v51 offset:7936
	ds_read_b128 v[14:17], v51 offset:8192
	v_add_f32_e32 v234, v232, v233
	v_pk_mul_f32 v[236:237], v[8:9], v[36:37]
	v_pk_fma_f32 v[236:237], v[6:7], v[34:35], v[236:237]
	v_add_f32_dpp v234, v234, v234 quad_perm:[1,0,3,2] row_mask:0xf bank_mask:0xf bound_ctrl:1
	s_waitcnt lgkmcnt(5)
	v_pk_mul_f32 v[228:229], v[64:65], v[34:35]
	v_add_f32_e32 v238, v236, v237
	v_add_f32_dpp v234, v234, v234 quad_perm:[2,3,0,1] row_mask:0xf bank_mask:0xf bound_ctrl:1
	v_pk_mul_f32 v[230:231], v[66:67], v[36:37]
	v_pk_fma_f32 v[56:57], v[68:69], v[242:243], v[228:229] op_sel_hi:[1,0,1]
	v_add_f32_dpp v234, v234, v234 row_half_mirror row_mask:0xf bank_mask:0xf bound_ctrl:1
	v_pk_fma_f32 v[54:55], v[70:71], v[242:243], v[230:231] op_sel_hi:[1,0,1]
	v_add_f32_dpp v238, v238, v238 quad_perm:[1,0,3,2] row_mask:0xf bank_mask:0xf bound_ctrl:1
	v_add_f32_dpp v234, v234, v234 row_mirror row_mask:0xf bank_mask:0xf bound_ctrl:1
	ds_read_b32 v240, v62 offset:8960
	ds_read_b128 v[10:13], v51 offset:8704
	ds_read_b128 v[6:9], v51 offset:7680
	s_waitcnt lgkmcnt(7)
	v_pk_fma_f32 v[36:37], v[32:33], v[234:235], v[54:55] op_sel_hi:[1,0,1]
	v_pk_fma_f32 v[34:35], v[30:31], v[234:235], v[56:57] op_sel_hi:[1,0,1]
	v_add_f32_dpp v238, v238, v238 quad_perm:[2,3,0,1] row_mask:0xf bank_mask:0xf bound_ctrl:1
	ds_write_b32 v49, v238 offset:768
	ds_read_b128 v[224:227], v51 offset:9984
	s_waitcnt lgkmcnt(6)
	v_pk_mul_f32 v[232:233], v[28:29], v[36:37]
	v_pk_fma_f32 v[232:233], v[26:27], v[34:35], v[232:233]
	ds_read_b128 v[64:67], v51 offset:9472
	ds_read_b128 v[68:71], v51 offset:9728
	v_add_f32_e32 v234, v232, v233
	v_pk_mul_f32 v[236:237], v[24:25], v[36:37]
	v_pk_fma_f32 v[236:237], v[22:23], v[34:35], v[236:237]
	v_add_f32_dpp v234, v234, v234 quad_perm:[1,0,3,2] row_mask:0xf bank_mask:0xf bound_ctrl:1
	s_waitcnt lgkmcnt(5)
	v_pk_mul_f32 v[228:229], v[18:19], v[34:35]
	v_add_f32_e32 v238, v236, v237
	v_add_f32_dpp v234, v234, v234 quad_perm:[2,3,0,1] row_mask:0xf bank_mask:0xf bound_ctrl:1
	v_pk_mul_f32 v[230:231], v[20:21], v[36:37]
	v_pk_fma_f32 v[56:57], v[14:15], v[240:241], v[228:229] op_sel_hi:[1,0,1]
	v_add_f32_dpp v234, v234, v234 row_half_mirror row_mask:0xf bank_mask:0xf bound_ctrl:1
	v_pk_fma_f32 v[54:55], v[16:17], v[240:241], v[230:231] op_sel_hi:[1,0,1]
	v_add_f32_dpp v238, v238, v238 quad_perm:[1,0,3,2] row_mask:0xf bank_mask:0xf bound_ctrl:1
	v_add_f32_dpp v234, v234, v234 row_mirror row_mask:0xf bank_mask:0xf bound_ctrl:1
	ds_read_b32 v242, v62 offset:10496
	ds_read_b128 v[30:33], v51 offset:10240
	ds_read_b128 v[22:25], v51 offset:9216
	s_waitcnt lgkmcnt(7)
	v_pk_fma_f32 v[36:37], v[12:13], v[234:235], v[54:55] op_sel_hi:[1,0,1]
	v_pk_fma_f32 v[34:35], v[10:11], v[234:235], v[56:57] op_sel_hi:[1,0,1]
	v_add_f32_dpp v238, v238, v238 quad_perm:[2,3,0,1] row_mask:0xf bank_mask:0xf bound_ctrl:1
	ds_write_b32 v49, v238 offset:1024
	ds_read_b128 v[26:29], v51 offset:11520
	s_waitcnt lgkmcnt(6)
	v_pk_mul_f32 v[232:233], v[226:227], v[36:37]
	v_pk_fma_f32 v[232:233], v[224:225], v[34:35], v[232:233]
	ds_read_b128 v[18:21], v51 offset:11008
	ds_read_b128 v[14:17], v51 offset:11264
	v_add_f32_e32 v234, v232, v233
	v_pk_mul_f32 v[236:237], v[8:9], v[36:37]
	v_pk_fma_f32 v[236:237], v[6:7], v[34:35], v[236:237]
	v_add_f32_dpp v234, v234, v234 quad_perm:[1,0,3,2] row_mask:0xf bank_mask:0xf bound_ctrl:1
	s_waitcnt lgkmcnt(5)
	v_pk_mul_f32 v[228:229], v[64:65], v[34:35]
	v_add_f32_e32 v238, v236, v237
	v_add_f32_dpp v234, v234, v234 quad_perm:[2,3,0,1] row_mask:0xf bank_mask:0xf bound_ctrl:1
	v_pk_mul_f32 v[230:231], v[66:67], v[36:37]
	v_pk_fma_f32 v[56:57], v[68:69], v[242:243], v[228:229] op_sel_hi:[1,0,1]
	v_add_f32_dpp v234, v234, v234 row_half_mirror row_mask:0xf bank_mask:0xf bound_ctrl:1
	v_pk_fma_f32 v[54:55], v[70:71], v[242:243], v[230:231] op_sel_hi:[1,0,1]
	v_add_f32_dpp v238, v238, v238 quad_perm:[1,0,3,2] row_mask:0xf bank_mask:0xf bound_ctrl:1
	v_add_f32_dpp v234, v234, v234 row_mirror row_mask:0xf bank_mask:0xf bound_ctrl:1
	ds_read_b32 v240, v62 offset:12032
	ds_read_b128 v[10:13], v51 offset:11776
	ds_read_b128 v[6:9], v51 offset:10752
	s_waitcnt lgkmcnt(7)
	v_pk_fma_f32 v[36:37], v[32:33], v[234:235], v[54:55] op_sel_hi:[1,0,1]
	v_pk_fma_f32 v[34:35], v[30:31], v[234:235], v[56:57] op_sel_hi:[1,0,1]
	v_add_f32_dpp v238, v238, v238 quad_perm:[2,3,0,1] row_mask:0xf bank_mask:0xf bound_ctrl:1
	ds_write_b32 v49, v238 offset:1280
	s_waitcnt lgkmcnt(5)
	v_pk_mul_f32 v[232:233], v[28:29], v[36:37]
	v_pk_fma_f32 v[232:233], v[26:27], v[34:35], v[232:233]
	v_add_f32_e32 v234, v232, v233
	v_pk_mul_f32 v[236:237], v[24:25], v[36:37]
	v_pk_fma_f32 v[236:237], v[22:23], v[34:35], v[236:237]
	v_add_f32_dpp v234, v234, v234 quad_perm:[1,0,3,2] row_mask:0xf bank_mask:0xf bound_ctrl:1
	s_waitcnt lgkmcnt(2)
	v_pk_mul_f32 v[228:229], v[18:19], v[34:35]
	v_add_f32_e32 v238, v236, v237
	v_add_f32_dpp v234, v234, v234 quad_perm:[2,3,0,1] row_mask:0xf bank_mask:0xf bound_ctrl:1
	v_pk_mul_f32 v[230:231], v[20:21], v[36:37]
	v_pk_fma_f32 v[56:57], v[14:15], v[240:241], v[228:229] op_sel_hi:[1,0,1]
	v_add_f32_dpp v234, v234, v234 row_half_mirror row_mask:0xf bank_mask:0xf bound_ctrl:1
	v_pk_fma_f32 v[54:55], v[16:17], v[240:241], v[230:231] op_sel_hi:[1,0,1]
	v_add_f32_dpp v238, v238, v238 quad_perm:[1,0,3,2] row_mask:0xf bank_mask:0xf bound_ctrl:1
	v_add_f32_dpp v234, v234, v234 row_mirror row_mask:0xf bank_mask:0xf bound_ctrl:1
	s_waitcnt lgkmcnt(1)
	v_pk_fma_f32 v[36:37], v[12:13], v[234:235], v[54:55] op_sel_hi:[1,0,1]
	v_pk_fma_f32 v[34:35], v[10:11], v[234:235], v[56:57] op_sel_hi:[1,0,1]
	v_add_f32_dpp v238, v238, v238 quad_perm:[2,3,0,1] row_mask:0xf bank_mask:0xf bound_ctrl:1
	ds_write_b32 v49, v238 offset:1536
	v_pk_mul_f32 v[236:237], v[8:9], v[36:37]
	v_pk_fma_f32 v[236:237], v[6:7], v[34:35], v[236:237]
	v_add_f32_e32 v238, v236, v237
	s_nop 1
	v_add_f32_dpp v52, v238, v238 quad_perm:[1,0,3,2] row_mask:0xf bank_mask:0xf bound_ctrl:1
	s_nop 1
	v_mov_b32_dpp v64, v52 quad_perm:[2,3,0,1] row_mask:0xf bank_mask:0xf bound_ctrl:1

.LBB0_1654:
	s_lshr_b32 s2, s57, 7
	v_readlane_b32 s3, v253, 2
	s_mul_i32 s2, s2, s3
	v_readlane_b32 s3, v253, 3
	s_add_i32 s2, s2, s3
	s_ashr_i32 s4, s2, 6
	s_bfe_u32 s28, s2, 0x40002
	s_lshl_b32 s2, s2, 4
	s_and_b32 s3, s57, 0x7f
	s_and_b32 s2, s2, 48
	s_cmpk_eq_i32 s3, 0x7f
	s_cselect_b64 s[26:27], -1, 0
	s_mov_b64 s[18:19], s[64:65]
	s_ashr_i32 s5, s4, 31
	s_lshl_b64 s[4:5], s[4:5], 4
	s_add_u32 s4, s4, s24
	s_addc_u32 s5, s5, s25
	s_or_b32 s4, s4, s28
	s_lshl_b64 s[4:5], s[4:5], 14
	s_waitcnt lgkmcnt(0)
	s_add_u32 s4, s18, s4
	s_addc_u32 s5, s19, s5
	s_lshl_b32 s18, s2, 8
	s_add_u32 s4, s4, s18
	s_addc_u32 s5, s5, 0
	s_add_u32 s28, s4, 0x4800000
	s_addc_u32 s29, s5, 0
	s_cmp_lg_u32 s3, 0
	s_cselect_b64 vcc, -1, 0
	v_cndmask_b32_e32 v37, 0, v5, vcc
	v_cndmask_b32_e32 v36, 0, v4, vcc
	v_cndmask_b32_e32 v35, 0, v3, vcc
	v_cndmask_b32_e32 v34, 0, v2, vcc
	s_and_b32 s3, s57, 3
	s_cbranch_execz .LBB0_1629
	s_branch .LBB0_1630
